# v29: v26 + SwiGLU epilogue re-associated: h = ag*au * rcp(fma(exp2(ag*nrs), m, m)), 4 VALU + 2 trans per output instead of 6 + 2
# speedup vs baseline: 1.0100x; 1.0046x over previous
; DI unsigned cvt_pk(float lo, float hi) { unsigned r; asm("v_cvt_pk_bf16_f32 %0, %1, %2" : "=v"(r) : "v"(lo), "v"(hi)); return r; }
; DI float siluf_(float x) { return x * sigmoidf_(x); }
;     __device__ __forceinline__ void operator()(const f32x4 (&acc)[2][2][4][2], const Unit& u, int wr, int wc, int fr, int fq) const {
;         const int row0 = u.pm * BM + wr * 64 + fr, col0 = u.pn * 128 + wc * 32 + 8 * fq;
; #pragma unroll
;         for (int ai = 0; ai < 2; ++ai)
; #pragma unroll
;             for (int m = 0; m < 4; ++m) {
;                 const int row = row0 + ai * HALF + m * 16;
;                 const float rs = rsqrtf(ss[row] * (1.f / DM) + EPS);
;                 float h[8];
; #pragma unroll
;                 for (int n = 0; n < 2; ++n)
; #pragma unroll
;                     for (int j = 0; j < 4; ++j) { const float gg = acc[ai][0][m][n][j] * rs, uu = acc[ai][1][m][n][j] * rs; h[4 * n + j] = siluf_(gg) * uu; }
;                 u32x4 w; w.x = cvt_pk(h[0], h[1]); w.y = cvt_pk(h[2], h[3]); w.z = cvt_pk(h[4], h[5]); w.w = cvt_pk(h[6], h[7]);
;                 *(u32x4*)(H + (size_t)row * DFF + col0) = w;
;             }
.LBB0_297:
	v_lshl_add_u32 v138, s41, 8, v155
	v_ashrrev_i32_e32 v139, 31, v138
	v_lshl_add_u64 v[140:141], v[138:139], 2, s[10:11]
	global_load_dword v139, v[140:141], off
	global_load_dword v162, v[140:141], off offset:64
	global_load_dword v163, v[140:141], off offset:128
	global_load_dword v164, v[140:141], off offset:192
	global_load_dword v165, v[140:141], off offset:512
	global_load_dword v166, v[140:141], off offset:576
	global_load_dword v167, v[140:141], off offset:640
	global_load_dword v168, v[140:141], off offset:704
	s_mov_b32 s15, 0x800000
	v_lshl_or_b32 v142, s40, 7, v157
	v_ashrrev_i32_e32 v143, 31, v142
	v_mov_b64_e32 v[186:187], s[8:9]
	v_lshlrev_b64 v[188:189], 1, v[142:143]
	s_waitcnt vmcnt(0)
	v_fmamk_f32 v180, v139, 0x3a800000, v217
	v_rsq_f32_e32 v181, v180
	v_add_u32_e32 v182, 0, v138
	v_mul_f32_e32 v181, 0xbfb8aa3b, v181
	v_mul_f32_e32 v172, v124, v181
	v_mul_f32_e32 v173, v125, v181
	v_mul_f32_e32 v174, v126, v181
	v_mul_f32_e32 v175, v127, v181
	v_mul_f32_e32 v176, v116, v181
	v_mul_f32_e32 v177, v117, v181
	v_mul_f32_e32 v178, v118, v181
	v_mul_f32_e32 v179, v119, v181
	v_exp_f32_e32 v172, v172
	v_exp_f32_e32 v173, v173
	v_exp_f32_e32 v174, v174
	v_exp_f32_e32 v175, v175
	v_exp_f32_e32 v176, v176
	v_exp_f32_e32 v177, v177
	v_exp_f32_e32 v178, v178
	v_exp_f32_e32 v179, v179
	v_mul_f32_e32 v124, v120, v124
	v_mul_f32_e32 v125, v121, v125
	v_mul_f32_e32 v126, v122, v126
	v_mul_f32_e32 v127, v123, v127
	v_mul_f32_e32 v116, v112, v116
	v_mul_f32_e32 v117, v113, v117
	v_mul_f32_e32 v118, v114, v118
	v_mul_f32_e32 v119, v115, v119
	v_fma_f32 v172, v172, v180, v180
	v_fma_f32 v173, v173, v180, v180
	v_fma_f32 v174, v174, v180, v180
	v_fma_f32 v175, v175, v180, v180
	v_fma_f32 v176, v176, v180, v180
	v_fma_f32 v177, v177, v180, v180
	v_fma_f32 v178, v178, v180, v180
	v_fma_f32 v179, v179, v180, v180
	v_rcp_f32_e32 v172, v172
	v_rcp_f32_e32 v173, v173
	v_rcp_f32_e32 v174, v174
	v_rcp_f32_e32 v175, v175
	v_rcp_f32_e32 v176, v176
	v_rcp_f32_e32 v177, v177
	v_rcp_f32_e32 v178, v178
	v_rcp_f32_e32 v179, v179
	v_mul_f32_e32 v124, v124, v172
	v_mul_f32_e32 v125, v125, v173
	v_mul_f32_e32 v126, v126, v174
	v_mul_f32_e32 v127, v127, v175
	v_mul_f32_e32 v116, v116, v176
	v_mul_f32_e32 v117, v117, v177
	v_mul_f32_e32 v118, v118, v178
	v_mul_f32_e32 v119, v119, v179
	v_mad_i64_i32 v[184:185], s[2:3], v182, s64, v[186:187]
	v_cvt_pk_bf16_f32 v172, v124, v125
	v_cvt_pk_bf16_f32 v173, v126, v127
	v_cvt_pk_bf16_f32 v174, v116, v117
	v_cvt_pk_bf16_f32 v175, v118, v119
	v_lshl_add_u64 v[184:185], v[184:185], 0, v[188:189]
	global_store_dwordx4 v[184:185], v[172:175], off
	v_fmamk_f32 v180, v162, 0x3a800000, v217
	v_rsq_f32_e32 v181, v180
	v_add_u32_e32 v182, 16, v138
	v_mul_f32_e32 v181, 0xbfb8aa3b, v181
	v_mul_f32_e32 v172, v108, v181
	v_mul_f32_e32 v173, v109, v181
	v_mul_f32_e32 v174, v110, v181
	v_mul_f32_e32 v175, v111, v181
	v_mul_f32_e32 v176, v100, v181
	v_mul_f32_e32 v177, v101, v181
	v_mul_f32_e32 v178, v102, v181
	v_mul_f32_e32 v179, v103, v181
	v_exp_f32_e32 v172, v172
	v_exp_f32_e32 v173, v173
	v_exp_f32_e32 v174, v174
	v_exp_f32_e32 v175, v175
	v_exp_f32_e32 v176, v176
	v_exp_f32_e32 v177, v177
	v_exp_f32_e32 v178, v178
	v_exp_f32_e32 v179, v179
	v_mul_f32_e32 v108, v104, v108
	v_mul_f32_e32 v109, v105, v109
	v_mul_f32_e32 v110, v106, v110
	v_mul_f32_e32 v111, v107, v111
	v_mul_f32_e32 v100, v96, v100
	v_mul_f32_e32 v101, v97, v101
	v_mul_f32_e32 v102, v98, v102
	v_mul_f32_e32 v103, v99, v103
	v_fma_f32 v172, v172, v180, v180
	v_fma_f32 v173, v173, v180, v180
	v_fma_f32 v174, v174, v180, v180
	v_fma_f32 v175, v175, v180, v180
	v_fma_f32 v176, v176, v180, v180
	v_fma_f32 v177, v177, v180, v180
	v_fma_f32 v178, v178, v180, v180
	v_fma_f32 v179, v179, v180, v180
	v_rcp_f32_e32 v172, v172
	v_rcp_f32_e32 v173, v173
	v_rcp_f32_e32 v174, v174
	v_rcp_f32_e32 v175, v175
	v_rcp_f32_e32 v176, v176
	v_rcp_f32_e32 v177, v177
	v_rcp_f32_e32 v178, v178
	v_rcp_f32_e32 v179, v179
	v_mul_f32_e32 v108, v108, v172
	v_mul_f32_e32 v109, v109, v173
	v_mul_f32_e32 v110, v110, v174
	v_mul_f32_e32 v111, v111, v175
	v_mul_f32_e32 v100, v100, v176
	v_mul_f32_e32 v101, v101, v177
	v_mul_f32_e32 v102, v102, v178
	v_mul_f32_e32 v103, v103, v179
	v_mad_i64_i32 v[184:185], s[2:3], v182, s64, v[186:187]
	v_cvt_pk_bf16_f32 v172, v108, v109
	v_cvt_pk_bf16_f32 v173, v110, v111
	v_cvt_pk_bf16_f32 v174, v100, v101
	v_cvt_pk_bf16_f32 v175, v102, v103
	v_lshl_add_u64 v[184:185], v[184:185], 0, v[188:189]
	global_store_dwordx4 v[184:185], v[172:175], off
	v_fmamk_f32 v180, v163, 0x3a800000, v217
	v_rsq_f32_e32 v181, v180
	v_add_u32_e32 v182, 32, v138
	v_mul_f32_e32 v181, 0xbfb8aa3b, v181
	v_mul_f32_e32 v172, v92, v181
	v_mul_f32_e32 v173, v93, v181
	v_mul_f32_e32 v174, v94, v181
	v_mul_f32_e32 v175, v95, v181
	v_mul_f32_e32 v176, v84, v181
	v_mul_f32_e32 v177, v85, v181
	v_mul_f32_e32 v178, v86, v181
	v_mul_f32_e32 v179, v87, v181
	v_exp_f32_e32 v172, v172
	v_exp_f32_e32 v173, v173
	v_exp_f32_e32 v174, v174
	v_exp_f32_e32 v175, v175
	v_exp_f32_e32 v176, v176
	v_exp_f32_e32 v177, v177
	v_exp_f32_e32 v178, v178
	v_exp_f32_e32 v179, v179
	v_mul_f32_e32 v92, v88, v92
	v_mul_f32_e32 v93, v89, v93
	v_mul_f32_e32 v94, v90, v94
	v_mul_f32_e32 v95, v91, v95
	v_mul_f32_e32 v84, v80, v84
	v_mul_f32_e32 v85, v81, v85
	v_mul_f32_e32 v86, v82, v86
	v_mul_f32_e32 v87, v83, v87
	v_fma_f32 v172, v172, v180, v180
	v_fma_f32 v173, v173, v180, v180
	v_fma_f32 v174, v174, v180, v180
	v_fma_f32 v175, v175, v180, v180
	v_fma_f32 v176, v176, v180, v180
	v_fma_f32 v177, v177, v180, v180
	v_fma_f32 v178, v178, v180, v180
	v_fma_f32 v179, v179, v180, v180
	v_rcp_f32_e32 v172, v172
; DI unsigned cvt_pk(float lo, float hi) { unsigned r; asm("v_cvt_pk_bf16_f32 %0, %1, %2" : "=v"(r) : "v"(lo), "v"(hi)); return r; }
; DI float siluf_(float x) { return x * sigmoidf_(x); }
;     __device__ __forceinline__ void operator()(const f32x4 (&acc)[2][2][4][2], const Unit& u, int wr, int wc, int fr, int fq) const {
;     ...
;             for (int m = 0; m < 4; ++m) {
;                 const int row = row0 + ai * HALF + m * 16;
;                 const float rs = rsqrtf(ss[row] * (1.f / DM) + EPS);
;                 float h[8];
; #pragma unroll
;                 for (int n = 0; n < 2; ++n)
; #pragma unroll
;                     for (int j = 0; j < 4; ++j) { const float gg = acc[ai][0][m][n][j] * rs, uu = acc[ai][1][m][n][j] * rs; h[4 * n + j] = siluf_(gg) * uu; }
;                 u32x4 w; w.x = cvt_pk(h[0], h[1]); w.y = cvt_pk(h[2], h[3]); w.z = cvt_pk(h[4], h[5]); w.w = cvt_pk(h[6], h[7]);
;                 *(u32x4*)(H + (size_t)row * DFF + col0) = w;
	v_rcp_f32_e32 v173, v173
	v_rcp_f32_e32 v174, v174
	v_rcp_f32_e32 v175, v175
	v_rcp_f32_e32 v176, v176
	v_rcp_f32_e32 v177, v177
	v_rcp_f32_e32 v178, v178
	v_rcp_f32_e32 v179, v179
	v_mul_f32_e32 v92, v92, v172
	v_mul_f32_e32 v93, v93, v173
	v_mul_f32_e32 v94, v94, v174
	v_mul_f32_e32 v95, v95, v175
	v_mul_f32_e32 v84, v84, v176
	v_mul_f32_e32 v85, v85, v177
	v_mul_f32_e32 v86, v86, v178
	v_mul_f32_e32 v87, v87, v179
	v_mad_i64_i32 v[184:185], s[2:3], v182, s64, v[186:187]
	v_cvt_pk_bf16_f32 v172, v92, v93
	v_cvt_pk_bf16_f32 v173, v94, v95
	v_cvt_pk_bf16_f32 v174, v84, v85
	v_cvt_pk_bf16_f32 v175, v86, v87
	v_lshl_add_u64 v[184:185], v[184:185], 0, v[188:189]
	global_store_dwordx4 v[184:185], v[172:175], off
	v_fmamk_f32 v180, v164, 0x3a800000, v217
	v_rsq_f32_e32 v181, v180
	v_add_u32_e32 v182, 48, v138
	v_mul_f32_e32 v181, 0xbfb8aa3b, v181
	v_mul_f32_e32 v172, v76, v181
	v_mul_f32_e32 v173, v77, v181
	v_mul_f32_e32 v174, v78, v181
	v_mul_f32_e32 v175, v79, v181
	v_mul_f32_e32 v176, v68, v181
	v_mul_f32_e32 v177, v69, v181
	v_mul_f32_e32 v178, v70, v181
	v_mul_f32_e32 v179, v71, v181
	v_exp_f32_e32 v172, v172
	v_exp_f32_e32 v173, v173
	v_exp_f32_e32 v174, v174
	v_exp_f32_e32 v175, v175
	v_exp_f32_e32 v176, v176
	v_exp_f32_e32 v177, v177
	v_exp_f32_e32 v178, v178
	v_exp_f32_e32 v179, v179
	v_mul_f32_e32 v76, v72, v76
	v_mul_f32_e32 v77, v73, v77
	v_mul_f32_e32 v78, v74, v78
	v_mul_f32_e32 v79, v75, v79
	v_mul_f32_e32 v68, v64, v68
	v_mul_f32_e32 v69, v65, v69
	v_mul_f32_e32 v70, v66, v70
	v_mul_f32_e32 v71, v67, v71
	v_fma_f32 v172, v172, v180, v180
	v_fma_f32 v173, v173, v180, v180
	v_fma_f32 v174, v174, v180, v180
	v_fma_f32 v175, v175, v180, v180
	v_fma_f32 v176, v176, v180, v180
	v_fma_f32 v177, v177, v180, v180
	v_fma_f32 v178, v178, v180, v180
	v_fma_f32 v179, v179, v180, v180
	v_rcp_f32_e32 v172, v172
	v_rcp_f32_e32 v173, v173
	v_rcp_f32_e32 v174, v174
	v_rcp_f32_e32 v175, v175
	v_rcp_f32_e32 v176, v176
	v_rcp_f32_e32 v177, v177
	v_rcp_f32_e32 v178, v178
	v_rcp_f32_e32 v179, v179
	v_mul_f32_e32 v76, v76, v172
	v_mul_f32_e32 v77, v77, v173
	v_mul_f32_e32 v78, v78, v174
	v_mul_f32_e32 v79, v79, v175
	v_mul_f32_e32 v68, v68, v176
	v_mul_f32_e32 v69, v69, v177
	v_mul_f32_e32 v70, v70, v178
	v_mul_f32_e32 v71, v71, v179
	v_mad_i64_i32 v[184:185], s[2:3], v182, s64, v[186:187]
	v_cvt_pk_bf16_f32 v172, v76, v77
	v_cvt_pk_bf16_f32 v173, v78, v79
	v_cvt_pk_bf16_f32 v174, v68, v69
	v_cvt_pk_bf16_f32 v175, v70, v71
	v_lshl_add_u64 v[184:185], v[184:185], 0, v[188:189]
	global_store_dwordx4 v[184:185], v[172:175], off
	v_fmamk_f32 v180, v165, 0x3a800000, v217
	v_rsq_f32_e32 v181, v180
	v_add_u32_e32 v182, 128, v138
	v_mul_f32_e32 v181, 0xbfb8aa3b, v181
	v_mul_f32_e32 v172, v60, v181
	v_mul_f32_e32 v173, v61, v181
	v_mul_f32_e32 v174, v62, v181
	v_mul_f32_e32 v175, v63, v181
	v_mul_f32_e32 v176, v52, v181
	v_mul_f32_e32 v177, v53, v181
	v_mul_f32_e32 v178, v54, v181
	v_mul_f32_e32 v179, v55, v181
	v_exp_f32_e32 v172, v172
	v_exp_f32_e32 v173, v173
	v_exp_f32_e32 v174, v174
	v_exp_f32_e32 v175, v175
	v_exp_f32_e32 v176, v176
	v_exp_f32_e32 v177, v177
	v_exp_f32_e32 v178, v178
	v_exp_f32_e32 v179, v179
	v_mul_f32_e32 v60, v56, v60
	v_mul_f32_e32 v61, v57, v61
	v_mul_f32_e32 v62, v58, v62
	v_mul_f32_e32 v63, v59, v63
	v_mul_f32_e32 v52, v48, v52
	v_mul_f32_e32 v53, v49, v53
	v_mul_f32_e32 v54, v50, v54
	v_mul_f32_e32 v55, v51, v55
	v_fma_f32 v172, v172, v180, v180
	v_fma_f32 v173, v173, v180, v180
	v_fma_f32 v174, v174, v180, v180
	v_fma_f32 v175, v175, v180, v180
	v_fma_f32 v176, v176, v180, v180
	v_fma_f32 v177, v177, v180, v180
	v_fma_f32 v178, v178, v180, v180
	v_fma_f32 v179, v179, v180, v180
	v_rcp_f32_e32 v172, v172
	v_rcp_f32_e32 v173, v173
	v_rcp_f32_e32 v174, v174
	v_rcp_f32_e32 v175, v175
	v_rcp_f32_e32 v176, v176
	v_rcp_f32_e32 v177, v177
	v_rcp_f32_e32 v178, v178
	v_rcp_f32_e32 v179, v179
	v_mul_f32_e32 v60, v60, v172
	v_mul_f32_e32 v61, v61, v173
	v_mul_f32_e32 v62, v62, v174
	v_mul_f32_e32 v63, v63, v175
	v_mul_f32_e32 v52, v52, v176
	v_mul_f32_e32 v53, v53, v177
	v_mul_f32_e32 v54, v54, v178
	v_mul_f32_e32 v55, v55, v179
	v_mad_i64_i32 v[184:185], s[2:3], v182, s64, v[186:187]
	v_cvt_pk_bf16_f32 v172, v60, v61
	v_cvt_pk_bf16_f32 v173, v62, v63
	v_cvt_pk_bf16_f32 v174, v52, v53
	v_cvt_pk_bf16_f32 v175, v54, v55
	v_lshl_add_u64 v[184:185], v[184:185], 0, v[188:189]
	global_store_dwordx4 v[184:185], v[172:175], off
	v_fmamk_f32 v180, v166, 0x3a800000, v217
	v_rsq_f32_e32 v181, v180
	v_add_u32_e32 v182, 144, v138
	v_mul_f32_e32 v181, 0xbfb8aa3b, v181
	v_mul_f32_e32 v172, v44, v181
	v_mul_f32_e32 v173, v45, v181
	v_mul_f32_e32 v174, v46, v181
	v_mul_f32_e32 v175, v47, v181
	v_mul_f32_e32 v176, v36, v181
	v_mul_f32_e32 v177, v37, v181
	v_mul_f32_e32 v178, v38, v181
	v_mul_f32_e32 v179, v39, v181
	v_exp_f32_e32 v172, v172
	v_exp_f32_e32 v173, v173
	v_exp_f32_e32 v174, v174
	v_exp_f32_e32 v175, v175
	v_exp_f32_e32 v176, v176
	v_exp_f32_e32 v177, v177
	v_exp_f32_e32 v178, v178
	v_exp_f32_e32 v179, v179
	v_mul_f32_e32 v44, v40, v44
; DI unsigned cvt_pk(float lo, float hi) { unsigned r; asm("v_cvt_pk_bf16_f32 %0, %1, %2" : "=v"(r) : "v"(lo), "v"(hi)); return r; }
; DI float siluf_(float x) { return x * sigmoidf_(x); }
;     __device__ __forceinline__ void operator()(const f32x4 (&acc)[2][2][4][2], const Unit& u, int wr, int wc, int fr, int fq) const {
;     ...
;             for (int m = 0; m < 4; ++m) {
;                 const int row = row0 + ai * HALF + m * 16;
;                 const float rs = rsqrtf(ss[row] * (1.f / DM) + EPS);
;                 float h[8];
; #pragma unroll
;                 for (int n = 0; n < 2; ++n)
; #pragma unroll
;                     for (int j = 0; j < 4; ++j) { const float gg = acc[ai][0][m][n][j] * rs, uu = acc[ai][1][m][n][j] * rs; h[4 * n + j] = siluf_(gg) * uu; }
;                 u32x4 w; w.x = cvt_pk(h[0], h[1]); w.y = cvt_pk(h[2], h[3]); w.z = cvt_pk(h[4], h[5]); w.w = cvt_pk(h[6], h[7]);
;                 *(u32x4*)(H + (size_t)row * DFF + col0) = w;
;             }
	v_mul_f32_e32 v45, v41, v45
	v_mul_f32_e32 v46, v42, v46
	v_mul_f32_e32 v47, v43, v47
	v_mul_f32_e32 v36, v32, v36
	v_mul_f32_e32 v37, v33, v37
	v_mul_f32_e32 v38, v34, v38
	v_mul_f32_e32 v39, v35, v39
	v_fma_f32 v172, v172, v180, v180
	v_fma_f32 v173, v173, v180, v180
	v_fma_f32 v174, v174, v180, v180
	v_fma_f32 v175, v175, v180, v180
	v_fma_f32 v176, v176, v180, v180
	v_fma_f32 v177, v177, v180, v180
	v_fma_f32 v178, v178, v180, v180
	v_fma_f32 v179, v179, v180, v180
	v_rcp_f32_e32 v172, v172
	v_rcp_f32_e32 v173, v173
	v_rcp_f32_e32 v174, v174
	v_rcp_f32_e32 v175, v175
	v_rcp_f32_e32 v176, v176
	v_rcp_f32_e32 v177, v177
	v_rcp_f32_e32 v178, v178
	v_rcp_f32_e32 v179, v179
	v_mul_f32_e32 v44, v44, v172
	v_mul_f32_e32 v45, v45, v173
	v_mul_f32_e32 v46, v46, v174
	v_mul_f32_e32 v47, v47, v175
	v_mul_f32_e32 v36, v36, v176
	v_mul_f32_e32 v37, v37, v177
	v_mul_f32_e32 v38, v38, v178
	v_mul_f32_e32 v39, v39, v179
	v_mad_i64_i32 v[184:185], s[2:3], v182, s64, v[186:187]
	v_cvt_pk_bf16_f32 v172, v44, v45
	v_cvt_pk_bf16_f32 v173, v46, v47
	v_cvt_pk_bf16_f32 v174, v36, v37
	v_cvt_pk_bf16_f32 v175, v38, v39
	v_lshl_add_u64 v[184:185], v[184:185], 0, v[188:189]
	global_store_dwordx4 v[184:185], v[172:175], off
	v_fmamk_f32 v180, v167, 0x3a800000, v217
	v_rsq_f32_e32 v181, v180
	v_add_u32_e32 v182, 160, v138
	v_mul_f32_e32 v181, 0xbfb8aa3b, v181
	v_mul_f32_e32 v172, v28, v181
	v_mul_f32_e32 v173, v29, v181
	v_mul_f32_e32 v174, v30, v181
	v_mul_f32_e32 v175, v31, v181
	v_mul_f32_e32 v176, v20, v181
	v_mul_f32_e32 v177, v21, v181
	v_mul_f32_e32 v178, v22, v181
	v_mul_f32_e32 v179, v23, v181
	v_exp_f32_e32 v172, v172
	v_exp_f32_e32 v173, v173
	v_exp_f32_e32 v174, v174
	v_exp_f32_e32 v175, v175
	v_exp_f32_e32 v176, v176
	v_exp_f32_e32 v177, v177
	v_exp_f32_e32 v178, v178
	v_exp_f32_e32 v179, v179
	v_mul_f32_e32 v28, v24, v28
	v_mul_f32_e32 v29, v25, v29
	v_mul_f32_e32 v30, v26, v30
	v_mul_f32_e32 v31, v27, v31
	v_mul_f32_e32 v20, v16, v20
	v_mul_f32_e32 v21, v17, v21
	v_mul_f32_e32 v22, v18, v22
	v_mul_f32_e32 v23, v19, v23
	v_fma_f32 v172, v172, v180, v180
	v_fma_f32 v173, v173, v180, v180
	v_fma_f32 v174, v174, v180, v180
	v_fma_f32 v175, v175, v180, v180
	v_fma_f32 v176, v176, v180, v180
	v_fma_f32 v177, v177, v180, v180
	v_fma_f32 v178, v178, v180, v180
	v_fma_f32 v179, v179, v180, v180
	v_rcp_f32_e32 v172, v172
	v_rcp_f32_e32 v173, v173
	v_rcp_f32_e32 v174, v174
	v_rcp_f32_e32 v175, v175
	v_rcp_f32_e32 v176, v176
	v_rcp_f32_e32 v177, v177
	v_rcp_f32_e32 v178, v178
	v_rcp_f32_e32 v179, v179
	v_mul_f32_e32 v28, v28, v172
	v_mul_f32_e32 v29, v29, v173
	v_mul_f32_e32 v30, v30, v174
	v_mul_f32_e32 v31, v31, v175
	v_mul_f32_e32 v20, v20, v176
	v_mul_f32_e32 v21, v21, v177
	v_mul_f32_e32 v22, v22, v178
	v_mul_f32_e32 v23, v23, v179
	v_mad_i64_i32 v[184:185], s[2:3], v182, s64, v[186:187]
	v_cvt_pk_bf16_f32 v172, v28, v29
	v_cvt_pk_bf16_f32 v173, v30, v31
	v_cvt_pk_bf16_f32 v174, v20, v21
	v_cvt_pk_bf16_f32 v175, v22, v23
	v_lshl_add_u64 v[184:185], v[184:185], 0, v[188:189]
	global_store_dwordx4 v[184:185], v[172:175], off
	v_fmamk_f32 v180, v168, 0x3a800000, v217
	v_rsq_f32_e32 v181, v180
	v_add_u32_e32 v182, 176, v138
	v_mul_f32_e32 v181, 0xbfb8aa3b, v181
	v_mul_f32_e32 v172, v12, v181
	v_mul_f32_e32 v173, v13, v181
	v_mul_f32_e32 v174, v14, v181
	v_mul_f32_e32 v175, v15, v181
	v_mul_f32_e32 v176, v4, v181
	v_mul_f32_e32 v177, v5, v181
	v_mul_f32_e32 v178, v6, v181
	v_mul_f32_e32 v179, v7, v181
	v_exp_f32_e32 v172, v172
	v_exp_f32_e32 v173, v173
	v_exp_f32_e32 v174, v174
	v_exp_f32_e32 v175, v175
	v_exp_f32_e32 v176, v176
	v_exp_f32_e32 v177, v177
	v_exp_f32_e32 v178, v178
	v_exp_f32_e32 v179, v179
	v_mul_f32_e32 v12, v8, v12
	v_mul_f32_e32 v13, v9, v13
	v_mul_f32_e32 v14, v10, v14
	v_mul_f32_e32 v15, v11, v15
	v_mul_f32_e32 v4, v0, v4
	v_mul_f32_e32 v5, v1, v5
	v_mul_f32_e32 v6, v2, v6
	v_mul_f32_e32 v7, v3, v7
	v_fma_f32 v172, v172, v180, v180
	v_fma_f32 v173, v173, v180, v180
	v_fma_f32 v174, v174, v180, v180
	v_fma_f32 v175, v175, v180, v180
	v_fma_f32 v176, v176, v180, v180
	v_fma_f32 v177, v177, v180, v180
	v_fma_f32 v178, v178, v180, v180
	v_fma_f32 v179, v179, v180, v180
	v_rcp_f32_e32 v172, v172
	v_rcp_f32_e32 v173, v173
	v_rcp_f32_e32 v174, v174
	v_rcp_f32_e32 v175, v175
	v_rcp_f32_e32 v176, v176
	v_rcp_f32_e32 v177, v177
	v_rcp_f32_e32 v178, v178
	v_rcp_f32_e32 v179, v179
	v_mul_f32_e32 v12, v12, v172
	v_mul_f32_e32 v13, v13, v173
	v_mul_f32_e32 v14, v14, v174
	v_mul_f32_e32 v15, v15, v175
	v_mul_f32_e32 v4, v4, v176
	v_mul_f32_e32 v5, v5, v177
	v_mul_f32_e32 v6, v6, v178
	v_mul_f32_e32 v7, v7, v179
	v_mad_i64_i32 v[184:185], s[2:3], v182, s64, v[186:187]
	v_cvt_pk_bf16_f32 v172, v12, v13
	v_cvt_pk_bf16_f32 v173, v14, v15
	v_cvt_pk_bf16_f32 v174, v4, v5
	v_cvt_pk_bf16_f32 v175, v6, v7
	v_lshl_add_u64 v[184:185], v[184:185], 0, v[188:189]
	global_store_dwordx4 v[184:185], v[172:175], off
	s_mov_b64 s[2:3], -1
	s_andn2_b64 vcc, exec, s[4:5]
	s_cbranch_vccnz .LBB0_286
	s_andn2_b64 vcc, exec, s[6:7]
	s_cbranch_vccnz .LBB0_285
	s_barrier
	s_branch .LBB0_285

; DI unsigned cvt_pk(float lo, float hi) { unsigned r; asm("v_cvt_pk_bf16_f32 %0, %1, %2" : "=v"(r) : "v"(lo), "v"(hi)); return r; }
; DI float siluf_(float x) { return x * sigmoidf_(x); }
;     __device__ __forceinline__ void operator()(const f32x4 (&acc)[2][2][4][2], const Unit& u, int wr, int wc, int fr, int fq) const {
;         const int row0 = u.pm * BM + wr * 64 + fr, col0 = u.pn * 128 + wc * 32 + 8 * fq;
; #pragma unroll
;         for (int ai = 0; ai < 2; ++ai)
; #pragma unroll
;             for (int m = 0; m < 4; ++m) {
;                 const int row = row0 + ai * HALF + m * 16;
;                 const float rs = rsqrtf(ss[row] * (1.f / DM) + EPS);
;                 float h[8];
; #pragma unroll
;                 for (int n = 0; n < 2; ++n)
; #pragma unroll
;                     for (int j = 0; j < 4; ++j) { const float gg = acc[ai][0][m][n][j] * rs, uu = acc[ai][1][m][n][j] * rs; h[4 * n + j] = siluf_(gg) * uu; }
;                 u32x4 w; w.x = cvt_pk(h[0], h[1]); w.y = cvt_pk(h[2], h[3]); w.z = cvt_pk(h[4], h[5]); w.w = cvt_pk(h[6], h[7]);
;                 *(u32x4*)(H + (size_t)row * DFF + col0) = w;
;             }
.LBB0_1298:
	v_lshl_add_u32 v138, s41, 8, v155
	v_ashrrev_i32_e32 v139, 31, v138
	v_lshl_add_u64 v[140:141], v[138:139], 2, s[10:11]
	global_load_dword v139, v[140:141], off
	global_load_dword v162, v[140:141], off offset:64
	global_load_dword v163, v[140:141], off offset:128
	global_load_dword v164, v[140:141], off offset:192
	global_load_dword v165, v[140:141], off offset:512
	global_load_dword v166, v[140:141], off offset:576
	global_load_dword v167, v[140:141], off offset:640
	global_load_dword v168, v[140:141], off offset:704
	s_mov_b32 s15, 0x800000
	v_lshl_or_b32 v142, s40, 7, v157
	v_ashrrev_i32_e32 v143, 31, v142
	v_mov_b64_e32 v[186:187], s[4:5]
	v_lshlrev_b64 v[188:189], 1, v[142:143]
	s_waitcnt vmcnt(0)
	v_fmamk_f32 v180, v139, 0x3a800000, v217
	v_rsq_f32_e32 v181, v180
	v_add_u32_e32 v182, 0, v138
	v_mul_f32_e32 v181, 0xbfb8aa3b, v181
	v_mul_f32_e32 v172, v124, v181
	v_mul_f32_e32 v173, v125, v181
	v_mul_f32_e32 v174, v126, v181
	v_mul_f32_e32 v175, v127, v181
	v_mul_f32_e32 v176, v116, v181
	v_mul_f32_e32 v177, v117, v181
	v_mul_f32_e32 v178, v118, v181
	v_mul_f32_e32 v179, v119, v181
	v_exp_f32_e32 v172, v172
	v_exp_f32_e32 v173, v173
	v_exp_f32_e32 v174, v174
	v_exp_f32_e32 v175, v175
	v_exp_f32_e32 v176, v176
	v_exp_f32_e32 v177, v177
	v_exp_f32_e32 v178, v178
	v_exp_f32_e32 v179, v179
	v_mul_f32_e32 v124, v120, v124
	v_mul_f32_e32 v125, v121, v125
	v_mul_f32_e32 v126, v122, v126
	v_mul_f32_e32 v127, v123, v127
	v_mul_f32_e32 v116, v112, v116
	v_mul_f32_e32 v117, v113, v117
	v_mul_f32_e32 v118, v114, v118
	v_mul_f32_e32 v119, v115, v119
	v_fma_f32 v172, v172, v180, v180
	v_fma_f32 v173, v173, v180, v180
	v_fma_f32 v174, v174, v180, v180
	v_fma_f32 v175, v175, v180, v180
	v_fma_f32 v176, v176, v180, v180
	v_fma_f32 v177, v177, v180, v180
	v_fma_f32 v178, v178, v180, v180
	v_fma_f32 v179, v179, v180, v180
	v_rcp_f32_e32 v172, v172
	v_rcp_f32_e32 v173, v173
	v_rcp_f32_e32 v174, v174
	v_rcp_f32_e32 v175, v175
	v_rcp_f32_e32 v176, v176
	v_rcp_f32_e32 v177, v177
	v_rcp_f32_e32 v178, v178
	v_rcp_f32_e32 v179, v179
	v_mul_f32_e32 v124, v124, v172
	v_mul_f32_e32 v125, v125, v173
	v_mul_f32_e32 v126, v126, v174
	v_mul_f32_e32 v127, v127, v175
	v_mul_f32_e32 v116, v116, v176
	v_mul_f32_e32 v117, v117, v177
	v_mul_f32_e32 v118, v118, v178
	v_mul_f32_e32 v119, v119, v179
	v_mad_i64_i32 v[184:185], s[22:23], v182, s64, v[186:187]
	v_cvt_pk_bf16_f32 v172, v124, v125
	v_cvt_pk_bf16_f32 v173, v126, v127
	v_cvt_pk_bf16_f32 v174, v116, v117
	v_cvt_pk_bf16_f32 v175, v118, v119
	v_lshl_add_u64 v[184:185], v[184:185], 0, v[188:189]
	global_store_dwordx4 v[184:185], v[172:175], off
	v_fmamk_f32 v180, v162, 0x3a800000, v217
	v_rsq_f32_e32 v181, v180
	v_add_u32_e32 v182, 16, v138
	v_mul_f32_e32 v181, 0xbfb8aa3b, v181
	v_mul_f32_e32 v172, v108, v181
	v_mul_f32_e32 v173, v109, v181
	v_mul_f32_e32 v174, v110, v181
	v_mul_f32_e32 v175, v111, v181
	v_mul_f32_e32 v176, v100, v181
	v_mul_f32_e32 v177, v101, v181
	v_mul_f32_e32 v178, v102, v181
	v_mul_f32_e32 v179, v103, v181
	v_exp_f32_e32 v172, v172
	v_exp_f32_e32 v173, v173
	v_exp_f32_e32 v174, v174
	v_exp_f32_e32 v175, v175
	v_exp_f32_e32 v176, v176
	v_exp_f32_e32 v177, v177
	v_exp_f32_e32 v178, v178
	v_exp_f32_e32 v179, v179
	v_mul_f32_e32 v108, v104, v108
	v_mul_f32_e32 v109, v105, v109
	v_mul_f32_e32 v110, v106, v110
	v_mul_f32_e32 v111, v107, v111
	v_mul_f32_e32 v100, v96, v100
	v_mul_f32_e32 v101, v97, v101
	v_mul_f32_e32 v102, v98, v102
	v_mul_f32_e32 v103, v99, v103
	v_fma_f32 v172, v172, v180, v180
	v_fma_f32 v173, v173, v180, v180
	v_fma_f32 v174, v174, v180, v180
	v_fma_f32 v175, v175, v180, v180
	v_fma_f32 v176, v176, v180, v180
	v_fma_f32 v177, v177, v180, v180
	v_fma_f32 v178, v178, v180, v180
	v_fma_f32 v179, v179, v180, v180
	v_rcp_f32_e32 v172, v172
	v_rcp_f32_e32 v173, v173
	v_rcp_f32_e32 v174, v174
	v_rcp_f32_e32 v175, v175
	v_rcp_f32_e32 v176, v176
	v_rcp_f32_e32 v177, v177
	v_rcp_f32_e32 v178, v178
	v_rcp_f32_e32 v179, v179
	v_mul_f32_e32 v108, v108, v172
	v_mul_f32_e32 v109, v109, v173
	v_mul_f32_e32 v110, v110, v174
	v_mul_f32_e32 v111, v111, v175
	v_mul_f32_e32 v100, v100, v176
	v_mul_f32_e32 v101, v101, v177
	v_mul_f32_e32 v102, v102, v178
	v_mul_f32_e32 v103, v103, v179
	v_mad_i64_i32 v[184:185], s[22:23], v182, s64, v[186:187]
	v_cvt_pk_bf16_f32 v172, v108, v109
	v_cvt_pk_bf16_f32 v173, v110, v111
	v_cvt_pk_bf16_f32 v174, v100, v101
	v_cvt_pk_bf16_f32 v175, v102, v103
	v_lshl_add_u64 v[184:185], v[184:185], 0, v[188:189]
	global_store_dwordx4 v[184:185], v[172:175], off
	v_fmamk_f32 v180, v163, 0x3a800000, v217
	v_rsq_f32_e32 v181, v180
	v_add_u32_e32 v182, 32, v138
	v_mul_f32_e32 v181, 0xbfb8aa3b, v181
	v_mul_f32_e32 v172, v92, v181
	v_mul_f32_e32 v173, v93, v181
	v_mul_f32_e32 v174, v94, v181
	v_mul_f32_e32 v175, v95, v181
	v_mul_f32_e32 v176, v84, v181
	v_mul_f32_e32 v177, v85, v181
	v_mul_f32_e32 v178, v86, v181
	v_mul_f32_e32 v179, v87, v181
	v_exp_f32_e32 v172, v172
	v_exp_f32_e32 v173, v173
	v_exp_f32_e32 v174, v174
	v_exp_f32_e32 v175, v175
	v_exp_f32_e32 v176, v176
	v_exp_f32_e32 v177, v177
	v_exp_f32_e32 v178, v178
	v_exp_f32_e32 v179, v179
	v_mul_f32_e32 v92, v88, v92
	v_mul_f32_e32 v93, v89, v93
	v_mul_f32_e32 v94, v90, v94
	v_mul_f32_e32 v95, v91, v95
	v_mul_f32_e32 v84, v80, v84
	v_mul_f32_e32 v85, v81, v85
	v_mul_f32_e32 v86, v82, v86
	v_mul_f32_e32 v87, v83, v87
	v_fma_f32 v172, v172, v180, v180
	v_fma_f32 v173, v173, v180, v180
	v_fma_f32 v174, v174, v180, v180
	v_fma_f32 v175, v175, v180, v180
	v_fma_f32 v176, v176, v180, v180
	v_fma_f32 v177, v177, v180, v180
	v_fma_f32 v178, v178, v180, v180
	v_fma_f32 v179, v179, v180, v180
	v_rcp_f32_e32 v172, v172
; DI unsigned cvt_pk(float lo, float hi) { unsigned r; asm("v_cvt_pk_bf16_f32 %0, %1, %2" : "=v"(r) : "v"(lo), "v"(hi)); return r; }
; DI float siluf_(float x) { return x * sigmoidf_(x); }
;     __device__ __forceinline__ void operator()(const f32x4 (&acc)[2][2][4][2], const Unit& u, int wr, int wc, int fr, int fq) const {
;     ...
;             for (int m = 0; m < 4; ++m) {
;                 const int row = row0 + ai * HALF + m * 16;
;                 const float rs = rsqrtf(ss[row] * (1.f / DM) + EPS);
;                 float h[8];
; #pragma unroll
;                 for (int n = 0; n < 2; ++n)
; #pragma unroll
;                     for (int j = 0; j < 4; ++j) { const float gg = acc[ai][0][m][n][j] * rs, uu = acc[ai][1][m][n][j] * rs; h[4 * n + j] = siluf_(gg) * uu; }
;                 u32x4 w; w.x = cvt_pk(h[0], h[1]); w.y = cvt_pk(h[2], h[3]); w.z = cvt_pk(h[4], h[5]); w.w = cvt_pk(h[6], h[7]);
;                 *(u32x4*)(H + (size_t)row * DFF + col0) = w;
	v_rcp_f32_e32 v173, v173
	v_rcp_f32_e32 v174, v174
	v_rcp_f32_e32 v175, v175
	v_rcp_f32_e32 v176, v176
	v_rcp_f32_e32 v177, v177
	v_rcp_f32_e32 v178, v178
	v_rcp_f32_e32 v179, v179
	v_mul_f32_e32 v92, v92, v172
	v_mul_f32_e32 v93, v93, v173
	v_mul_f32_e32 v94, v94, v174
	v_mul_f32_e32 v95, v95, v175
	v_mul_f32_e32 v84, v84, v176
	v_mul_f32_e32 v85, v85, v177
	v_mul_f32_e32 v86, v86, v178
	v_mul_f32_e32 v87, v87, v179
	v_mad_i64_i32 v[184:185], s[22:23], v182, s64, v[186:187]
	v_cvt_pk_bf16_f32 v172, v92, v93
	v_cvt_pk_bf16_f32 v173, v94, v95
	v_cvt_pk_bf16_f32 v174, v84, v85
	v_cvt_pk_bf16_f32 v175, v86, v87
	v_lshl_add_u64 v[184:185], v[184:185], 0, v[188:189]
	global_store_dwordx4 v[184:185], v[172:175], off
	v_fmamk_f32 v180, v164, 0x3a800000, v217
	v_rsq_f32_e32 v181, v180
	v_add_u32_e32 v182, 48, v138
	v_mul_f32_e32 v181, 0xbfb8aa3b, v181
	v_mul_f32_e32 v172, v76, v181
	v_mul_f32_e32 v173, v77, v181
	v_mul_f32_e32 v174, v78, v181
	v_mul_f32_e32 v175, v79, v181
	v_mul_f32_e32 v176, v68, v181
	v_mul_f32_e32 v177, v69, v181
	v_mul_f32_e32 v178, v70, v181
	v_mul_f32_e32 v179, v71, v181
	v_exp_f32_e32 v172, v172
	v_exp_f32_e32 v173, v173
	v_exp_f32_e32 v174, v174
	v_exp_f32_e32 v175, v175
	v_exp_f32_e32 v176, v176
	v_exp_f32_e32 v177, v177
	v_exp_f32_e32 v178, v178
	v_exp_f32_e32 v179, v179
	v_mul_f32_e32 v76, v72, v76
	v_mul_f32_e32 v77, v73, v77
	v_mul_f32_e32 v78, v74, v78
	v_mul_f32_e32 v79, v75, v79
	v_mul_f32_e32 v68, v64, v68
	v_mul_f32_e32 v69, v65, v69
	v_mul_f32_e32 v70, v66, v70
	v_mul_f32_e32 v71, v67, v71
	v_fma_f32 v172, v172, v180, v180
	v_fma_f32 v173, v173, v180, v180
	v_fma_f32 v174, v174, v180, v180
	v_fma_f32 v175, v175, v180, v180
	v_fma_f32 v176, v176, v180, v180
	v_fma_f32 v177, v177, v180, v180
	v_fma_f32 v178, v178, v180, v180
	v_fma_f32 v179, v179, v180, v180
	v_rcp_f32_e32 v172, v172
	v_rcp_f32_e32 v173, v173
	v_rcp_f32_e32 v174, v174
	v_rcp_f32_e32 v175, v175
	v_rcp_f32_e32 v176, v176
	v_rcp_f32_e32 v177, v177
	v_rcp_f32_e32 v178, v178
	v_rcp_f32_e32 v179, v179
	v_mul_f32_e32 v76, v76, v172
	v_mul_f32_e32 v77, v77, v173
	v_mul_f32_e32 v78, v78, v174
	v_mul_f32_e32 v79, v79, v175
	v_mul_f32_e32 v68, v68, v176
	v_mul_f32_e32 v69, v69, v177
	v_mul_f32_e32 v70, v70, v178
	v_mul_f32_e32 v71, v71, v179
	v_mad_i64_i32 v[184:185], s[22:23], v182, s64, v[186:187]
	v_cvt_pk_bf16_f32 v172, v76, v77
	v_cvt_pk_bf16_f32 v173, v78, v79
	v_cvt_pk_bf16_f32 v174, v68, v69
	v_cvt_pk_bf16_f32 v175, v70, v71
	v_lshl_add_u64 v[184:185], v[184:185], 0, v[188:189]
	global_store_dwordx4 v[184:185], v[172:175], off
	v_fmamk_f32 v180, v165, 0x3a800000, v217
	v_rsq_f32_e32 v181, v180
	v_add_u32_e32 v182, 128, v138
	v_mul_f32_e32 v181, 0xbfb8aa3b, v181
	v_mul_f32_e32 v172, v60, v181
	v_mul_f32_e32 v173, v61, v181
	v_mul_f32_e32 v174, v62, v181
	v_mul_f32_e32 v175, v63, v181
	v_mul_f32_e32 v176, v52, v181
	v_mul_f32_e32 v177, v53, v181
	v_mul_f32_e32 v178, v54, v181
	v_mul_f32_e32 v179, v55, v181
	v_exp_f32_e32 v172, v172
	v_exp_f32_e32 v173, v173
	v_exp_f32_e32 v174, v174
	v_exp_f32_e32 v175, v175
	v_exp_f32_e32 v176, v176
	v_exp_f32_e32 v177, v177
	v_exp_f32_e32 v178, v178
	v_exp_f32_e32 v179, v179
	v_mul_f32_e32 v60, v56, v60
	v_mul_f32_e32 v61, v57, v61
	v_mul_f32_e32 v62, v58, v62
	v_mul_f32_e32 v63, v59, v63
	v_mul_f32_e32 v52, v48, v52
	v_mul_f32_e32 v53, v49, v53
	v_mul_f32_e32 v54, v50, v54
	v_mul_f32_e32 v55, v51, v55
	v_fma_f32 v172, v172, v180, v180
	v_fma_f32 v173, v173, v180, v180
	v_fma_f32 v174, v174, v180, v180
	v_fma_f32 v175, v175, v180, v180
	v_fma_f32 v176, v176, v180, v180
	v_fma_f32 v177, v177, v180, v180
	v_fma_f32 v178, v178, v180, v180
	v_fma_f32 v179, v179, v180, v180
	v_rcp_f32_e32 v172, v172
	v_rcp_f32_e32 v173, v173
	v_rcp_f32_e32 v174, v174
	v_rcp_f32_e32 v175, v175
	v_rcp_f32_e32 v176, v176
	v_rcp_f32_e32 v177, v177
	v_rcp_f32_e32 v178, v178
	v_rcp_f32_e32 v179, v179
	v_mul_f32_e32 v60, v60, v172
	v_mul_f32_e32 v61, v61, v173
	v_mul_f32_e32 v62, v62, v174
	v_mul_f32_e32 v63, v63, v175
	v_mul_f32_e32 v52, v52, v176
	v_mul_f32_e32 v53, v53, v177
	v_mul_f32_e32 v54, v54, v178
	v_mul_f32_e32 v55, v55, v179
	v_mad_i64_i32 v[184:185], s[22:23], v182, s64, v[186:187]
	v_cvt_pk_bf16_f32 v172, v60, v61
	v_cvt_pk_bf16_f32 v173, v62, v63
	v_cvt_pk_bf16_f32 v174, v52, v53
	v_cvt_pk_bf16_f32 v175, v54, v55
	v_lshl_add_u64 v[184:185], v[184:185], 0, v[188:189]
	global_store_dwordx4 v[184:185], v[172:175], off
	v_fmamk_f32 v180, v166, 0x3a800000, v217
	v_rsq_f32_e32 v181, v180
	v_add_u32_e32 v182, 144, v138
	v_mul_f32_e32 v181, 0xbfb8aa3b, v181
	v_mul_f32_e32 v172, v44, v181
	v_mul_f32_e32 v173, v45, v181
	v_mul_f32_e32 v174, v46, v181
	v_mul_f32_e32 v175, v47, v181
	v_mul_f32_e32 v176, v36, v181
	v_mul_f32_e32 v177, v37, v181
	v_mul_f32_e32 v178, v38, v181
	v_mul_f32_e32 v179, v39, v181
	v_exp_f32_e32 v172, v172
	v_exp_f32_e32 v173, v173
	v_exp_f32_e32 v174, v174
	v_exp_f32_e32 v175, v175
	v_exp_f32_e32 v176, v176
	v_exp_f32_e32 v177, v177
	v_exp_f32_e32 v178, v178
	v_exp_f32_e32 v179, v179
	v_mul_f32_e32 v44, v40, v44
; DI unsigned cvt_pk(float lo, float hi) { unsigned r; asm("v_cvt_pk_bf16_f32 %0, %1, %2" : "=v"(r) : "v"(lo), "v"(hi)); return r; }
; DI float siluf_(float x) { return x * sigmoidf_(x); }
;     __device__ __forceinline__ void operator()(const f32x4 (&acc)[2][2][4][2], const Unit& u, int wr, int wc, int fr, int fq) const {
;     ...
;             for (int m = 0; m < 4; ++m) {
;                 const int row = row0 + ai * HALF + m * 16;
;                 const float rs = rsqrtf(ss[row] * (1.f / DM) + EPS);
;                 float h[8];
; #pragma unroll
;                 for (int n = 0; n < 2; ++n)
; #pragma unroll
;                     for (int j = 0; j < 4; ++j) { const float gg = acc[ai][0][m][n][j] * rs, uu = acc[ai][1][m][n][j] * rs; h[4 * n + j] = siluf_(gg) * uu; }
;                 u32x4 w; w.x = cvt_pk(h[0], h[1]); w.y = cvt_pk(h[2], h[3]); w.z = cvt_pk(h[4], h[5]); w.w = cvt_pk(h[6], h[7]);
;                 *(u32x4*)(H + (size_t)row * DFF + col0) = w;
;             }
	v_mul_f32_e32 v45, v41, v45
	v_mul_f32_e32 v46, v42, v46
	v_mul_f32_e32 v47, v43, v47
	v_mul_f32_e32 v36, v32, v36
	v_mul_f32_e32 v37, v33, v37
	v_mul_f32_e32 v38, v34, v38
	v_mul_f32_e32 v39, v35, v39
	v_fma_f32 v172, v172, v180, v180
	v_fma_f32 v173, v173, v180, v180
	v_fma_f32 v174, v174, v180, v180
	v_fma_f32 v175, v175, v180, v180
	v_fma_f32 v176, v176, v180, v180
	v_fma_f32 v177, v177, v180, v180
	v_fma_f32 v178, v178, v180, v180
	v_fma_f32 v179, v179, v180, v180
	v_rcp_f32_e32 v172, v172
	v_rcp_f32_e32 v173, v173
	v_rcp_f32_e32 v174, v174
	v_rcp_f32_e32 v175, v175
	v_rcp_f32_e32 v176, v176
	v_rcp_f32_e32 v177, v177
	v_rcp_f32_e32 v178, v178
	v_rcp_f32_e32 v179, v179
	v_mul_f32_e32 v44, v44, v172
	v_mul_f32_e32 v45, v45, v173
	v_mul_f32_e32 v46, v46, v174
	v_mul_f32_e32 v47, v47, v175
	v_mul_f32_e32 v36, v36, v176
	v_mul_f32_e32 v37, v37, v177
	v_mul_f32_e32 v38, v38, v178
	v_mul_f32_e32 v39, v39, v179
	v_mad_i64_i32 v[184:185], s[22:23], v182, s64, v[186:187]
	v_cvt_pk_bf16_f32 v172, v44, v45
	v_cvt_pk_bf16_f32 v173, v46, v47
	v_cvt_pk_bf16_f32 v174, v36, v37
	v_cvt_pk_bf16_f32 v175, v38, v39
	v_lshl_add_u64 v[184:185], v[184:185], 0, v[188:189]
	global_store_dwordx4 v[184:185], v[172:175], off
	v_fmamk_f32 v180, v167, 0x3a800000, v217
	v_rsq_f32_e32 v181, v180
	v_add_u32_e32 v182, 160, v138
	v_mul_f32_e32 v181, 0xbfb8aa3b, v181
	v_mul_f32_e32 v172, v28, v181
	v_mul_f32_e32 v173, v29, v181
	v_mul_f32_e32 v174, v30, v181
	v_mul_f32_e32 v175, v31, v181
	v_mul_f32_e32 v176, v20, v181
	v_mul_f32_e32 v177, v21, v181
	v_mul_f32_e32 v178, v22, v181
	v_mul_f32_e32 v179, v23, v181
	v_exp_f32_e32 v172, v172
	v_exp_f32_e32 v173, v173
	v_exp_f32_e32 v174, v174
	v_exp_f32_e32 v175, v175
	v_exp_f32_e32 v176, v176
	v_exp_f32_e32 v177, v177
	v_exp_f32_e32 v178, v178
	v_exp_f32_e32 v179, v179
	v_mul_f32_e32 v28, v24, v28
	v_mul_f32_e32 v29, v25, v29
	v_mul_f32_e32 v30, v26, v30
	v_mul_f32_e32 v31, v27, v31
	v_mul_f32_e32 v20, v16, v20
	v_mul_f32_e32 v21, v17, v21
	v_mul_f32_e32 v22, v18, v22
	v_mul_f32_e32 v23, v19, v23
	v_fma_f32 v172, v172, v180, v180
	v_fma_f32 v173, v173, v180, v180
	v_fma_f32 v174, v174, v180, v180
	v_fma_f32 v175, v175, v180, v180
	v_fma_f32 v176, v176, v180, v180
	v_fma_f32 v177, v177, v180, v180
	v_fma_f32 v178, v178, v180, v180
	v_fma_f32 v179, v179, v180, v180
	v_rcp_f32_e32 v172, v172
	v_rcp_f32_e32 v173, v173
	v_rcp_f32_e32 v174, v174
	v_rcp_f32_e32 v175, v175
	v_rcp_f32_e32 v176, v176
	v_rcp_f32_e32 v177, v177
	v_rcp_f32_e32 v178, v178
	v_rcp_f32_e32 v179, v179
	v_mul_f32_e32 v28, v28, v172
	v_mul_f32_e32 v29, v29, v173
	v_mul_f32_e32 v30, v30, v174
	v_mul_f32_e32 v31, v31, v175
	v_mul_f32_e32 v20, v20, v176
	v_mul_f32_e32 v21, v21, v177
	v_mul_f32_e32 v22, v22, v178
	v_mul_f32_e32 v23, v23, v179
	v_mad_i64_i32 v[184:185], s[22:23], v182, s64, v[186:187]
	v_cvt_pk_bf16_f32 v172, v28, v29
	v_cvt_pk_bf16_f32 v173, v30, v31
	v_cvt_pk_bf16_f32 v174, v20, v21
	v_cvt_pk_bf16_f32 v175, v22, v23
	v_lshl_add_u64 v[184:185], v[184:185], 0, v[188:189]
	global_store_dwordx4 v[184:185], v[172:175], off
	v_fmamk_f32 v180, v168, 0x3a800000, v217
	v_rsq_f32_e32 v181, v180
	v_add_u32_e32 v182, 176, v138
	v_mul_f32_e32 v181, 0xbfb8aa3b, v181
	v_mul_f32_e32 v172, v12, v181
	v_mul_f32_e32 v173, v13, v181
	v_mul_f32_e32 v174, v14, v181
	v_mul_f32_e32 v175, v15, v181
	v_mul_f32_e32 v176, v4, v181
	v_mul_f32_e32 v177, v5, v181
	v_mul_f32_e32 v178, v6, v181
	v_mul_f32_e32 v179, v7, v181
	v_exp_f32_e32 v172, v172
	v_exp_f32_e32 v173, v173
	v_exp_f32_e32 v174, v174
	v_exp_f32_e32 v175, v175
	v_exp_f32_e32 v176, v176
	v_exp_f32_e32 v177, v177
	v_exp_f32_e32 v178, v178
	v_exp_f32_e32 v179, v179
	v_mul_f32_e32 v12, v8, v12
	v_mul_f32_e32 v13, v9, v13
	v_mul_f32_e32 v14, v10, v14
	v_mul_f32_e32 v15, v11, v15
	v_mul_f32_e32 v4, v0, v4
	v_mul_f32_e32 v5, v1, v5
	v_mul_f32_e32 v6, v2, v6
	v_mul_f32_e32 v7, v3, v7
	v_fma_f32 v172, v172, v180, v180
	v_fma_f32 v173, v173, v180, v180
	v_fma_f32 v174, v174, v180, v180
	v_fma_f32 v175, v175, v180, v180
	v_fma_f32 v176, v176, v180, v180
	v_fma_f32 v177, v177, v180, v180
	v_fma_f32 v178, v178, v180, v180
	v_fma_f32 v179, v179, v180, v180
	v_rcp_f32_e32 v172, v172
	v_rcp_f32_e32 v173, v173
	v_rcp_f32_e32 v174, v174
	v_rcp_f32_e32 v175, v175
	v_rcp_f32_e32 v176, v176
	v_rcp_f32_e32 v177, v177
	v_rcp_f32_e32 v178, v178
	v_rcp_f32_e32 v179, v179
	v_mul_f32_e32 v12, v12, v172
	v_mul_f32_e32 v13, v13, v173
	v_mul_f32_e32 v14, v14, v174
	v_mul_f32_e32 v15, v15, v175
	v_mul_f32_e32 v4, v4, v176
	v_mul_f32_e32 v5, v5, v177
	v_mul_f32_e32 v6, v6, v178
	v_mul_f32_e32 v7, v7, v179
	v_mad_i64_i32 v[184:185], s[22:23], v182, s64, v[186:187]
	v_cvt_pk_bf16_f32 v172, v12, v13
	v_cvt_pk_bf16_f32 v173, v14, v15
	v_cvt_pk_bf16_f32 v174, v4, v5
	v_cvt_pk_bf16_f32 v175, v6, v7
	v_lshl_add_u64 v[184:185], v[184:185], 0, v[188:189]
	global_store_dwordx4 v[184:185], v[172:175], off
	s_mov_b64 s[22:23], -1
	s_andn2_b64 vcc, exec, s[6:7]
	s_cbranch_vccnz .LBB0_1287
	s_andn2_b64 vcc, exec, s[2:3]
	s_cbranch_vccnz .LBB0_1286
	s_barrier
	s_branch .LBB0_1286
